# D8: staging pieces at the start of the softmax section and after PV MFMAs 1,2,3 (FoX gate piece after MFMA 4)
# speedup vs baseline: 1.0202x; 1.0004x over previous
.LBB0_672:
	s_nop 7
	s_mul_i32 s16, s4, 0x4a00
	v_or_b32_e32 v252, s16, v125
	v_add_u32_e32 v253, v252, v137
	s_waitcnt vmcnt(3)
	ds_write_b128 v253, v[100:103]
	global_load_dwordx4 v[100:103], v228, s[10:11]
	v_exp_f32_e32 v2, v48
	v_exp_f32_e32 v3, v49
	v_exp_f32_e32 v4, v50
	v_exp_f32_e32 v5, v51
	v_add_f32_e32 v0, 0, v2
	v_exp_f32_e32 v6, v52
	v_add_f32_e32 v0, v3, v0
	v_exp_f32_e32 v7, v53
	v_add_f32_e32 v0, v4, v0
	v_exp_f32_e32 v8, v54
	v_add_f32_e32 v0, v5, v0
	v_exp_f32_e32 v9, v55
	v_add_f32_e32 v0, v6, v0
	v_add_f32_e32 v0, v7, v0
	v_exp_f32_e32 v50, v60
	v_exp_f32_e32 v60, v70
	v_add3_u32 v70, s6, v143, v145
	v_add_f32_e32 v0, v8, v0
	v_exp_f32_e32 v51, v61
	v_exp_f32_e32 v61, v71
	v_add_u32_e32 v71, 0x2000, v70
	v_add_f32_e32 v0, v9, v0
	v_cvt_pk_bf16_f32 v2, v2, v3
	v_cvt_pk_bf16_f32 v3, v4, v5
	v_cvt_pk_bf16_f32 v4, v6, v7
	v_cvt_pk_bf16_f32 v5, v8, v9
	ds_read2_b64 v[6:9], v71 offset0:128 offset1:130
	ds_read2_b64 v[10:13], v71 offset0:132 offset1:134
	v_add_u32_e32 v70, 0x3000, v70
	s_waitcnt lgkmcnt(1)
	v_mfma_f32_32x32x16_bf16 v[32:47], v[6:9], v[2:5], v[32:47]
	v_add3_u32 v253, v252, v138, s33
	s_waitcnt vmcnt(2)
	ds_write2_b64 v253, v[104:105], v[106:107] offset1:1
	global_load_dwordx4 v[104:107], v230, s[22:23]
	ds_read2_b64 v[6:9], v70 offset0:160 offset1:162
	v_exp_f32_e32 v14, v56
	v_exp_f32_e32 v15, v57
	v_exp_f32_e32 v48, v58
	v_exp_f32_e32 v49, v59
	v_exp_f32_e32 v52, v62
	v_exp_f32_e32 v53, v63
	s_waitcnt lgkmcnt(0)
	v_mfma_f32_32x32x16_bf16 v[16:31], v[6:9], v[2:5], v[16:31]
	v_add_u32_e32 v253, v252, v139
	s_waitcnt vmcnt(3)
	ds_write_b128 v253, v[108:111]
	global_load_dwordx4 v[108:111], v229, s[10:11]
	ds_read2_b64 v[6:9], v70 offset0:164 offset1:166
	v_cvt_pk_bf16_f32 v2, v14, v15
	v_cvt_pk_bf16_f32 v3, v48, v49
	v_cvt_pk_bf16_f32 v4, v50, v51
	v_cvt_pk_bf16_f32 v5, v52, v53
	v_exp_f32_e32 v54, v64
	v_exp_f32_e32 v55, v65
	s_waitcnt lgkmcnt(0)
	v_mfma_f32_32x32x16_bf16 v[16:31], v[6:9], v[2:5], v[16:31]
	v_add3_u32 v253, v252, v140, s33
	s_waitcnt vmcnt(3)
	ds_write2_b64 v253, v[112:113], v[114:115] offset1:1
	global_load_dwordx4 v[112:115], v231, s[22:23]
	s_add_u32 s10, s10, 0x2000
	s_addc_u32 s11, s11, 0
	s_add_u32 s22, s22, 0x80
	s_addc_u32 s23, s23, 0
	ds_read2_b64 v[6:9], v71 offset0:136 offset1:138
	v_exp_f32_e32 v56, v66
	v_exp_f32_e32 v57, v67
	v_exp_f32_e32 v58, v68
	v_exp_f32_e32 v59, v69
	v_add_f32_e32 v0, v14, v0
	v_add_f32_e32 v0, v15, v0
	v_mfma_f32_32x32x16_bf16 v[32:47], v[10:13], v[2:5], v[32:47]
	s_and_saveexec_b64 s[0:1], s[38:39]
	s_cbranch_execz .Ld5f_noga
	s_waitcnt vmcnt(4)
	v_xor_b32_e32 v239, 0x80000000, v99
	v_xor_b32_e32 v238, 0x80000000, v98
	v_xor_b32_e32 v237, 0x80000000, v97
	v_xor_b32_e32 v236, 0x80000000, v96
	v_add_u32_e32 v253, s16, v119
	ds_write_b128 v253, v[236:239] offset:18432
	global_load_dwordx4 v[96:99], v228, s[24:25]
.Ld5f_noga:
	s_or_b64 exec, exec, s[0:1]
	s_add_u32 s24, s24, 0x100
	s_addc_u32 s25, s25, 0
	v_cvt_pk_bf16_f32 v2, v54, v55
	v_cvt_pk_bf16_f32 v3, v56, v57
	v_cvt_pk_bf16_f32 v4, v58, v59
	v_cvt_pk_bf16_f32 v5, v60, v61
	v_add_f32_e32 v0, v48, v0
	v_add_f32_e32 v0, v49, v0
	v_exp_f32_e32 v62, v72
	s_waitcnt lgkmcnt(0)
	v_mfma_f32_32x32x16_bf16 v[32:47], v[6:9], v[2:5], v[32:47]
	ds_read2_b64 v[6:9], v70 offset0:168 offset1:170
	v_exp_f32_e32 v63, v73
	v_exp_f32_e32 v64, v74
	v_exp_f32_e32 v65, v75
	v_exp_f32_e32 v66, v76
	v_exp_f32_e32 v67, v77
	v_exp_f32_e32 v68, v78
	s_waitcnt lgkmcnt(0)
	v_mfma_f32_32x32x16_bf16 v[16:31], v[6:9], v[2:5], v[16:31]
	ds_read2_b64 v[6:9], v71 offset0:140 offset1:142
	v_exp_f32_e32 v69, v79
	v_add_f32_e32 v0, v50, v0
	v_add_f32_e32 v0, v51, v0
	v_add_f32_e32 v0, v52, v0
	v_add_f32_e32 v0, v53, v0
	v_cvt_pk_bf16_f32 v2, v62, v63
	v_cvt_pk_bf16_f32 v3, v64, v65
	v_cvt_pk_bf16_f32 v4, v66, v67
	v_cvt_pk_bf16_f32 v5, v68, v69
	v_add_f32_e32 v0, v54, v0
	v_add_f32_e32 v0, v55, v0
	s_waitcnt lgkmcnt(0)
	v_mfma_f32_32x32x16_bf16 v[32:47], v[6:9], v[2:5], v[32:47]
	ds_read2_b64 v[6:9], v70 offset0:172 offset1:174
	v_add_f32_e32 v0, v56, v0
	v_add_f32_e32 v0, v57, v0
	v_add_f32_e32 v0, v58, v0
	v_add_f32_e32 v0, v59, v0
	v_add_f32_e32 v0, v60, v0
	v_add_f32_e32 v0, v61, v0
	v_add_f32_e32 v0, v62, v0
	v_add_f32_e32 v0, v63, v0
	s_waitcnt lgkmcnt(0)
	v_mfma_f32_32x32x16_bf16 v[16:31], v[6:9], v[2:5], v[16:31]
	v_add_f32_e32 v0, v64, v0
	v_add_f32_e32 v0, v65, v0
	v_add_f32_e32 v0, v66, v0
	v_add_f32_e32 v0, v67, v0
	v_add_f32_e32 v0, v68, v0
	v_add_f32_e32 v0, v69, v0
	v_add_f32_e32 v142, v142, v0
	v_cmp_lt_f32_e32 vcc, s20, v0
	s_cbranch_vccz .LBB0_674
	v_mov_b32_e32 v2, v0
	s_nop 1
	v_permlane32_swap_b32_e32 v0, v2
	v_add_f32_e32 v0, v0, v2
	v_log_f32_e32 v2, v0
	v_cmp_lt_f32_e32 vcc, s20, v0
	s_nop 1
	v_cndmask_b32_e32 v2, 0, v2, vcc
	v_exp_f32_e64 v0, -v2
	v_add_f32_e32 v148, v148, v2
	v_xor_b32_e32 v136, 0x80000000, v148
	v_mul_f32_e32 v142, v142, v0
	v_pk_mul_f32 v[46:47], v[46:47], v[0:1] op_sel_hi:[1,0]
	v_pk_mul_f32 v[44:45], v[44:45], v[0:1] op_sel_hi:[1,0]
	v_pk_mul_f32 v[42:43], v[42:43], v[0:1] op_sel_hi:[1,0]
	v_pk_mul_f32 v[40:41], v[40:41], v[0:1] op_sel_hi:[1,0]
	v_pk_mul_f32 v[38:39], v[38:39], v[0:1] op_sel_hi:[1,0]
	v_pk_mul_f32 v[36:37], v[36:37], v[0:1] op_sel_hi:[1,0]
	v_pk_mul_f32 v[34:35], v[34:35], v[0:1] op_sel_hi:[1,0]
	v_pk_mul_f32 v[32:33], v[32:33], v[0:1] op_sel_hi:[1,0]
	v_pk_mul_f32 v[30:31], v[30:31], v[0:1] op_sel_hi:[1,0]
	v_pk_mul_f32 v[28:29], v[28:29], v[0:1] op_sel_hi:[1,0]
	v_pk_mul_f32 v[26:27], v[26:27], v[0:1] op_sel_hi:[1,0]
	v_pk_mul_f32 v[24:25], v[24:25], v[0:1] op_sel_hi:[1,0]
	v_pk_mul_f32 v[22:23], v[22:23], v[0:1] op_sel_hi:[1,0]
	v_pk_mul_f32 v[20:21], v[20:21], v[0:1] op_sel_hi:[1,0]
	v_pk_mul_f32 v[18:19], v[18:19], v[0:1] op_sel_hi:[1,0]
	v_pk_mul_f32 v[16:17], v[16:17], v[0:1] op_sel_hi:[1,0]
	s_branch .LBB0_674

.LBB0_705:
	s_nop 7
	s_mul_i32 s1, s9, 0x4a00
	v_or_b32_e32 v184, s1, v131
	v_add_u32_e32 v185, v184, v133
	s_waitcnt vmcnt(3)
	ds_write_b128 v185, v[108:111]
	global_load_dwordx4 v[108:111], v180, s[10:11]
	v_exp_f32_e32 v2, v80
	v_exp_f32_e32 v3, v81
	v_exp_f32_e32 v4, v82
	v_exp_f32_e32 v5, v83
	v_add_f32_e32 v0, 0, v2
	v_exp_f32_e32 v6, v84
	v_add_f32_e32 v0, v3, v0
	v_exp_f32_e32 v7, v85
	v_add_f32_e32 v0, v4, v0
	v_exp_f32_e32 v8, v86
	v_add_f32_e32 v0, v5, v0
	v_exp_f32_e32 v9, v87
	v_add_f32_e32 v0, v6, v0
	v_add_f32_e32 v0, v7, v0
	v_add3_u32 v86, s14, v147, v149
	v_add_f32_e32 v0, v8, v0
	v_add_u32_e32 v87, 0x2000, v86
	v_add_f32_e32 v0, v9, v0
	v_cvt_pk_bf16_f32 v2, v2, v3
	v_cvt_pk_bf16_f32 v3, v4, v5
	v_cvt_pk_bf16_f32 v4, v6, v7
	v_cvt_pk_bf16_f32 v5, v8, v9
	ds_read2_b64 v[6:9], v87 offset0:128 offset1:130
	ds_read2_b64 v[10:13], v87 offset0:132 offset1:134
	v_add_u32_e32 v86, 0x3000, v86
	s_waitcnt lgkmcnt(1)
	v_mfma_f32_32x32x16_bf16 v[32:47], v[6:9], v[2:5], v[32:47]
	v_add3_u32 v185, v184, v144, s33
	s_waitcnt vmcnt(2)
	ds_write2_b64 v185, v[104:105], v[106:107] offset1:1
	global_load_dwordx4 v[104:107], v182, s[16:17]
	ds_read2_b64 v[6:9], v86 offset0:160 offset1:162
	v_exp_f32_e32 v14, v88
	v_exp_f32_e32 v15, v89
	v_exp_f32_e32 v80, v90
	v_exp_f32_e32 v81, v91
	v_exp_f32_e32 v82, v92
	v_exp_f32_e32 v83, v93
	s_waitcnt lgkmcnt(0)
	v_mfma_f32_32x32x16_bf16 v[16:31], v[6:9], v[2:5], v[16:31]
	v_add_u32_e32 v185, v184, v145
	s_waitcnt vmcnt(3)
	ds_write_b128 v185, v[112:115]
	global_load_dwordx4 v[112:115], v181, s[10:11]
	ds_read2_b64 v[6:9], v86 offset0:164 offset1:166
	v_exp_f32_e32 v84, v94
	v_exp_f32_e32 v85, v95
	v_cvt_pk_bf16_f32 v2, v14, v15
	v_cvt_pk_bf16_f32 v3, v80, v81
	v_cvt_pk_bf16_f32 v4, v82, v83
	v_cvt_pk_bf16_f32 v5, v84, v85
	v_exp_f32_e32 v64, v64
	v_exp_f32_e32 v65, v65
	s_waitcnt lgkmcnt(0)
	v_mfma_f32_32x32x16_bf16 v[16:31], v[6:9], v[2:5], v[16:31]
	v_add3_u32 v185, v184, v146, s33
	s_waitcnt vmcnt(3)
	ds_write2_b64 v185, v[116:117], v[118:119] offset1:1
	global_load_dwordx4 v[116:119], v183, s[16:17]
	s_add_u32 s10, s10, 0x2000
	s_addc_u32 s11, s11, 0
	s_add_u32 s16, s16, 0x80
	s_addc_u32 s17, s17, 0
	ds_read2_b64 v[6:9], v87 offset0:136 offset1:138
	v_exp_f32_e32 v66, v66
	v_exp_f32_e32 v67, v67
	v_exp_f32_e32 v68, v68
	v_exp_f32_e32 v69, v69
	v_exp_f32_e32 v70, v70
	v_exp_f32_e32 v71, v71
	v_mfma_f32_32x32x16_bf16 v[32:47], v[10:13], v[2:5], v[32:47]
	v_cvt_pk_bf16_f32 v2, v64, v65
	v_cvt_pk_bf16_f32 v3, v66, v67
	v_cvt_pk_bf16_f32 v4, v68, v69
	v_cvt_pk_bf16_f32 v5, v70, v71
	v_add_f32_e32 v0, v14, v0
	v_add_f32_e32 v0, v15, v0
	v_add_f32_e32 v0, v80, v0
	s_waitcnt lgkmcnt(0)
	v_mfma_f32_32x32x16_bf16 v[32:47], v[6:9], v[2:5], v[32:47]
	ds_read2_b64 v[6:9], v86 offset0:168 offset1:170
	v_add_f32_e32 v0, v81, v0
	v_exp_f32_e32 v72, v72
	v_exp_f32_e32 v73, v73
	v_exp_f32_e32 v74, v74
	v_exp_f32_e32 v75, v75
	v_exp_f32_e32 v76, v76
	s_waitcnt lgkmcnt(0)
	v_mfma_f32_32x32x16_bf16 v[16:31], v[6:9], v[2:5], v[16:31]
	ds_read2_b64 v[6:9], v87 offset0:140 offset1:142
	v_exp_f32_e32 v77, v77
	v_exp_f32_e32 v78, v78
	v_exp_f32_e32 v79, v79
	v_add_f32_e32 v0, v82, v0
	v_add_f32_e32 v0, v83, v0
	v_add_f32_e32 v0, v84, v0
	v_add_f32_e32 v0, v85, v0
	v_cvt_pk_bf16_f32 v2, v72, v73
	v_cvt_pk_bf16_f32 v3, v74, v75
	v_cvt_pk_bf16_f32 v4, v76, v77
	v_cvt_pk_bf16_f32 v5, v78, v79
	v_add_f32_e32 v0, v64, v0
	v_add_f32_e32 v0, v65, v0
	s_waitcnt lgkmcnt(0)
	v_mfma_f32_32x32x16_bf16 v[32:47], v[6:9], v[2:5], v[32:47]
	ds_read2_b64 v[6:9], v86 offset0:172 offset1:174
	v_add_f32_e32 v0, v66, v0
	v_add_f32_e32 v0, v67, v0
	v_add_f32_e32 v0, v68, v0
	v_add_f32_e32 v0, v69, v0
	v_add_f32_e32 v0, v70, v0
	v_add_f32_e32 v0, v71, v0
	v_add_f32_e32 v0, v72, v0
	v_add_f32_e32 v0, v73, v0
	s_waitcnt lgkmcnt(0)
	v_mfma_f32_32x32x16_bf16 v[16:31], v[6:9], v[2:5], v[16:31]
	v_add_f32_e32 v0, v74, v0
	v_add_f32_e32 v0, v75, v0
	v_add_f32_e32 v0, v76, v0
	v_add_f32_e32 v0, v77, v0
	v_add_f32_e32 v0, v78, v0
	v_add_f32_e32 v0, v79, v0
	v_add_f32_e32 v152, v152, v0
	v_cmp_lt_f32_e32 vcc, s20, v0
	s_cbranch_vccz .LBB0_707
	v_mov_b32_e32 v2, v0
	s_nop 1
	v_permlane32_swap_b32_e32 v0, v2
	v_add_f32_e32 v0, v0, v2
	v_log_f32_e32 v2, v0
	v_cmp_lt_f32_e32 vcc, s20, v0
	s_nop 1
	v_cndmask_b32_e32 v2, 0, v2, vcc
	v_exp_f32_e64 v0, -v2
	v_add_f32_e32 v153, v153, v2
	v_xor_b32_e32 v63, 0x80000000, v153
	v_mov_b32_e32 v62, v63
	v_mul_f32_e32 v152, v152, v0
	v_pk_mul_f32 v[46:47], v[46:47], v[0:1] op_sel_hi:[1,0]
	v_pk_mul_f32 v[44:45], v[44:45], v[0:1] op_sel_hi:[1,0]
	v_pk_mul_f32 v[42:43], v[42:43], v[0:1] op_sel_hi:[1,0]
	v_pk_mul_f32 v[40:41], v[40:41], v[0:1] op_sel_hi:[1,0]
	v_pk_mul_f32 v[38:39], v[38:39], v[0:1] op_sel_hi:[1,0]
	v_pk_mul_f32 v[36:37], v[36:37], v[0:1] op_sel_hi:[1,0]
	v_pk_mul_f32 v[34:35], v[34:35], v[0:1] op_sel_hi:[1,0]
	v_pk_mul_f32 v[32:33], v[32:33], v[0:1] op_sel_hi:[1,0]
	v_pk_mul_f32 v[30:31], v[30:31], v[0:1] op_sel_hi:[1,0]
	v_pk_mul_f32 v[28:29], v[28:29], v[0:1] op_sel_hi:[1,0]
	v_pk_mul_f32 v[26:27], v[26:27], v[0:1] op_sel_hi:[1,0]
	v_pk_mul_f32 v[24:25], v[24:25], v[0:1] op_sel_hi:[1,0]
	v_pk_mul_f32 v[22:23], v[22:23], v[0:1] op_sel_hi:[1,0]
	v_pk_mul_f32 v[20:21], v[20:21], v[0:1] op_sel_hi:[1,0]
	v_pk_mul_f32 v[18:19], v[18:19], v[0:1] op_sel_hi:[1,0]
	v_pk_mul_f32 v[16:17], v[16:17], v[0:1] op_sel_hi:[1,0]
	v_mov_b32_e32 v61, v63
	v_mov_b32_e32 v60, v63
	v_mov_b32_e32 v59, v63
	v_mov_b32_e32 v58, v63
	v_mov_b32_e32 v57, v63
	v_mov_b32_e32 v56, v63
	v_mov_b32_e32 v55, v63
	v_mov_b32_e32 v54, v63
	v_mov_b32_e32 v53, v63
	v_mov_b32_e32 v52, v63
	v_mov_b32_e32 v51, v63
	v_mov_b32_e32 v50, v63
	v_mov_b32_e32 v49, v63
	v_mov_b32_e32 v48, v63
	s_branch .LBB0_707

.LBB0_919:
	s_nop 7
	s_mul_i32 s23, s17, 0x4a00
	v_or_b32_e32 v252, s23, v129
	v_add_u32_e32 v253, v252, v131
	s_waitcnt vmcnt(3)
	ds_write_b128 v253, v[98:101]
	global_load_dwordx4 v[98:101], v228, s[12:13]
	v_exp_f32_e32 v66, v66
	v_exp_f32_e32 v67, v67
	v_exp_f32_e32 v68, v68
	v_exp_f32_e32 v69, v69
	v_add_f32_e32 v147, 0, v66
	v_exp_f32_e32 v70, v70
	v_add_f32_e32 v147, v67, v147
	v_exp_f32_e32 v71, v71
	v_add_f32_e32 v147, v68, v147
	v_exp_f32_e32 v72, v72
	v_add_f32_e32 v147, v69, v147
	v_exp_f32_e32 v73, v73
	v_add_f32_e32 v147, v70, v147
	v_exp_f32_e32 v74, v74
	v_add_f32_e32 v147, v71, v147
	v_exp_f32_e32 v75, v75
	v_add_f32_e32 v147, v72, v147
	v_exp_f32_e32 v76, v76
	v_add_f32_e32 v147, v73, v147
	v_exp_f32_e32 v77, v77
	v_add_f32_e32 v147, v74, v147
	v_exp_f32_e32 v78, v78
	v_add_f32_e32 v147, v75, v147
	v_exp_f32_e32 v79, v79
	v_add_f32_e32 v147, v76, v147
	v_exp_f32_e32 v80, v80
	v_add_f32_e32 v147, v77, v147
	v_exp_f32_e32 v81, v81
	v_add_f32_e32 v147, v78, v147
	v_exp_f32_e32 v148, v50
	v_add_f32_e32 v147, v79, v147
	v_exp_f32_e32 v149, v51
	v_add_f32_e32 v50, v80, v147
	v_add_f32_e32 v50, v81, v50
	v_add3_u32 v153, s22, v181, v187
	v_add_f32_e32 v50, v148, v50
	v_add_u32_e32 v154, 0x2000, v153
	v_add_f32_e32 v147, v149, v50
	v_exp_f32_e32 v150, v52
	v_exp_f32_e32 v151, v53
	ds_read2_b64 v[50:53], v154 offset0:128 offset1:130
	v_add_u32_e32 v153, 0x3000, v153
	v_exp_f32_e32 v152, v54
	v_cvt_pk_bf16_f32 v54, v66, v67
	v_cvt_pk_bf16_f32 v66, v68, v69
	v_cvt_pk_bf16_f32 v67, v70, v71
	v_cvt_pk_bf16_f32 v68, v72, v73
	ds_read2_b64 v[70:73], v153 offset0:160 offset1:162
	v_cndmask_b32_e64 v69, 0, v68, s[0:1]
	v_cndmask_b32_e64 v68, 0, v67, s[0:1]
	v_cndmask_b32_e64 v67, 0, v66, s[0:1]
	v_cndmask_b32_e64 v66, 0, v54, s[0:1]
	v_exp_f32_e32 v155, v55
	v_exp_f32_e32 v193, v56
	s_waitcnt lgkmcnt(1)
	v_mfma_f32_32x32x16_bf16 v[18:33], v[50:53], v[66:69], v[18:33]
	v_add3_u32 v253, v252, v185, s33
	s_waitcnt vmcnt(2)
	ds_write2_b64 v253, v[102:103], v[104:105] offset1:1
	global_load_dwordx4 v[102:105], v230, s[24:25]
	v_add_f32_e32 v50, v150, v147
	v_add_f32_e32 v50, v151, v50
	v_add_f32_e32 v147, v152, v50
	ds_read2_b64 v[50:53], v154 offset0:132 offset1:134
	v_exp_f32_e32 v194, v57
	v_cvt_pk_bf16_f32 v54, v74, v75
	v_cvt_pk_bf16_f32 v55, v76, v77
	s_waitcnt lgkmcnt(1)
	v_mfma_f32_32x32x16_bf16 v[2:17], v[70:73], v[66:69], v[2:17]
	v_add_u32_e32 v253, v252, v180
	s_waitcnt vmcnt(3)
	ds_write_b128 v253, v[106:109]
	global_load_dwordx4 v[106:109], v229, s[12:13]
	ds_read2_b64 v[66:69], v153 offset0:164 offset1:166
	v_cvt_pk_bf16_f32 v56, v78, v79
	v_cvt_pk_bf16_f32 v57, v80, v81
	v_cndmask_b32_e64 v57, 0, v57, s[0:1]
	v_cndmask_b32_e64 v56, 0, v56, s[0:1]
	v_cndmask_b32_e64 v55, 0, v55, s[0:1]
	v_cndmask_b32_e64 v54, 0, v54, s[0:1]
	v_exp_f32_e32 v58, v58
	v_exp_f32_e32 v59, v59
	s_waitcnt lgkmcnt(1)
	v_mfma_f32_32x32x16_bf16 v[18:33], v[50:53], v[54:57], v[18:33]
	v_add3_u32 v253, v252, v186, s33
	s_waitcnt vmcnt(3)
	ds_write2_b64 v253, v[110:111], v[112:113] offset1:1
	global_load_dwordx4 v[110:113], v231, s[24:25]
	s_add_u32 s12, s12, 0x2000
	s_addc_u32 s13, s13, 0
	s_add_u32 s24, s24, 0x80
	s_addc_u32 s25, s25, 0
	v_add_f32_e32 v50, v155, v147
	v_add_f32_e32 v50, v193, v50
	v_add_f32_e32 v50, v194, v50
	v_add_f32_e32 v70, v58, v50
	ds_read2_b64 v[50:53], v154 offset0:136 offset1:138
	v_exp_f32_e32 v60, v60
	v_exp_f32_e32 v71, v61
	s_waitcnt lgkmcnt(1)
	v_mfma_f32_32x32x16_bf16 v[2:17], v[66:69], v[54:57], v[2:17]
	ds_read2_b64 v[66:69], v153 offset0:168 offset1:170
	v_cvt_pk_bf16_f32 v54, v148, v149
	v_cvt_pk_bf16_f32 v55, v150, v151
	v_cvt_pk_bf16_f32 v56, v152, v155
	v_cvt_pk_bf16_f32 v57, v193, v194
	v_cndmask_b32_e64 v57, 0, v57, s[0:1]
	v_cndmask_b32_e64 v56, 0, v56, s[0:1]
	v_cndmask_b32_e64 v55, 0, v55, s[0:1]
	v_cndmask_b32_e64 v54, 0, v54, s[0:1]
	v_exp_f32_e32 v62, v62
	v_exp_f32_e32 v63, v63
	s_waitcnt lgkmcnt(1)
	v_mfma_f32_32x32x16_bf16 v[18:33], v[50:53], v[54:57], v[18:33]
	v_add_f32_e32 v50, v59, v70
	v_add_f32_e32 v70, v60, v50
	ds_read2_b64 v[50:53], v154 offset0:140 offset1:142
	v_exp_f32_e32 v64, v64
	v_exp_f32_e32 v65, v65
	s_waitcnt lgkmcnt(1)
	v_mfma_f32_32x32x16_bf16 v[2:17], v[66:69], v[54:57], v[2:17]
	v_cvt_pk_bf16_f32 v54, v58, v59
	v_cvt_pk_bf16_f32 v55, v60, v71
	ds_read2_b64 v[58:61], v153 offset0:172 offset1:174
	v_cvt_pk_bf16_f32 v56, v62, v63
	v_cvt_pk_bf16_f32 v57, v64, v65
	v_cndmask_b32_e64 v57, 0, v57, s[0:1]
	v_cndmask_b32_e64 v56, 0, v56, s[0:1]
	v_cndmask_b32_e64 v55, 0, v55, s[0:1]
	v_cndmask_b32_e64 v54, 0, v54, s[0:1]
	s_waitcnt lgkmcnt(1)
	s_nop 0
	v_mfma_f32_32x32x16_bf16 v[18:33], v[50:53], v[54:57], v[18:33]
	v_add_f32_e32 v50, v71, v70
	v_add_f32_e32 v50, v62, v50
	v_add_f32_e32 v50, v63, v50
	v_add_f32_e32 v50, v64, v50
	v_add_f32_e32 v50, v65, v50
	v_cndmask_b32_e64 v50, 0, v50, s[0:1]
	v_add_f32_e32 v133, v133, v50
	s_waitcnt lgkmcnt(0)
	v_mfma_f32_32x32x16_bf16 v[2:17], v[58:61], v[54:57], v[2:17]
	v_cmp_lt_f32_e32 vcc, s20, v50
	s_cbranch_vccz .LBB0_921
	v_mov_b32_e32 v34, v50
	s_nop 1
	v_permlane32_swap_b32_e32 v50, v34
	v_add_f32_e32 v34, v50, v34
	v_log_f32_e32 v35, v34
	v_cmp_lt_f32_e32 vcc, s20, v34
	s_nop 1
	v_cndmask_b32_e32 v35, 0, v35, vcc
	v_exp_f32_e64 v34, -v35
	v_add_f32_e32 v135, v135, v35
	v_xor_b32_e32 v49, 0x80000000, v135
	v_mov_b32_e32 v48, v49
	v_mul_f32_e32 v133, v133, v34
	v_pk_mul_f32 v[32:33], v[32:33], v[34:35] op_sel_hi:[1,0]
	v_pk_mul_f32 v[30:31], v[30:31], v[34:35] op_sel_hi:[1,0]
	v_pk_mul_f32 v[28:29], v[28:29], v[34:35] op_sel_hi:[1,0]
	v_pk_mul_f32 v[26:27], v[26:27], v[34:35] op_sel_hi:[1,0]
	v_pk_mul_f32 v[24:25], v[24:25], v[34:35] op_sel_hi:[1,0]
	v_pk_mul_f32 v[22:23], v[22:23], v[34:35] op_sel_hi:[1,0]
	v_pk_mul_f32 v[20:21], v[20:21], v[34:35] op_sel_hi:[1,0]
	v_pk_mul_f32 v[18:19], v[18:19], v[34:35] op_sel_hi:[1,0]
	v_pk_mul_f32 v[16:17], v[16:17], v[34:35] op_sel_hi:[1,0]
	v_pk_mul_f32 v[14:15], v[14:15], v[34:35] op_sel_hi:[1,0]
	v_pk_mul_f32 v[12:13], v[12:13], v[34:35] op_sel_hi:[1,0]
	v_pk_mul_f32 v[10:11], v[10:11], v[34:35] op_sel_hi:[1,0]
	v_pk_mul_f32 v[8:9], v[8:9], v[34:35] op_sel_hi:[1,0]
	v_pk_mul_f32 v[6:7], v[6:7], v[34:35] op_sel_hi:[1,0]
	v_pk_mul_f32 v[4:5], v[4:5], v[34:35] op_sel_hi:[1,0]
	v_pk_mul_f32 v[2:3], v[2:3], v[34:35] op_sel_hi:[1,0]
	v_mov_b32_e32 v47, v49
	v_mov_b32_e32 v46, v49
	v_mov_b32_e32 v45, v49
	v_mov_b32_e32 v44, v49
	v_mov_b32_e32 v43, v49
	v_mov_b32_e32 v42, v49
	v_mov_b32_e32 v41, v49
	v_mov_b32_e32 v40, v49
	v_mov_b32_e32 v39, v49
	v_mov_b32_e32 v38, v49
	v_mov_b32_e32 v37, v49
	v_mov_b32_e32 v36, v49
	v_mov_b32_e32 v35, v49
	v_mov_b32_e32 v34, v49
	s_branch .LBB0_921

.LBB0_936:
	s_nop 4
	s_mul_i32 s22, s15, 0x4a00
	v_or_b32_e32 v252, s22, v129
	v_add_u32_e32 v253, v252, v131
	s_waitcnt vmcnt(3)
	ds_write_b128 v253, v[98:101]
	global_load_dwordx4 v[98:101], v228, s[12:13]
	v_exp_f32_e32 v66, v66
	v_exp_f32_e32 v67, v67
	v_exp_f32_e32 v68, v68
	v_exp_f32_e32 v69, v69
	v_add_f32_e32 v138, 0, v66
	v_exp_f32_e32 v70, v70
	v_add_f32_e32 v138, v67, v138
	v_exp_f32_e32 v71, v71
	v_add_f32_e32 v138, v68, v138
	v_exp_f32_e32 v72, v72
	v_add_f32_e32 v138, v69, v138
	v_exp_f32_e32 v73, v73
	v_add_f32_e32 v138, v70, v138
	v_exp_f32_e32 v74, v74
	v_add_f32_e32 v138, v71, v138
	v_exp_f32_e32 v75, v75
	v_add_f32_e32 v138, v72, v138
	v_exp_f32_e32 v76, v76
	v_add_f32_e32 v138, v73, v138
	v_exp_f32_e32 v77, v77
	v_add_f32_e32 v138, v74, v138
	v_exp_f32_e32 v78, v78
	v_add_f32_e32 v138, v75, v138
	v_exp_f32_e32 v79, v79
	v_add_f32_e32 v138, v76, v138
	v_exp_f32_e32 v80, v80
	v_add_f32_e32 v138, v77, v138
	v_exp_f32_e32 v81, v81
	v_add_f32_e32 v138, v78, v138
	v_exp_f32_e32 v139, v50
	v_add_f32_e32 v138, v79, v138
	v_add_f32_e32 v138, v80, v138
	v_add_f32_e32 v138, v81, v138
	v_add_f32_e32 v50, v139, v138
	v_exp_f32_e32 v138, v52
	v_cvt_pk_bf16_f32 v52, v66, v67
	v_add3_u32 v66, s16, v181, v187
	v_add_u32_e32 v67, 0x2000, v66
	v_exp_f32_e32 v143, v56
	v_exp_f32_e32 v144, v57
	v_exp_f32_e32 v145, v58
	v_exp_f32_e32 v147, v59
	v_exp_f32_e32 v148, v60
	v_exp_f32_e32 v149, v61
	v_exp_f32_e32 v150, v62
	v_exp_f32_e32 v151, v63
	ds_read2_b64 v[56:59], v67 offset0:128 offset1:130
	ds_read2_b64 v[60:63], v67 offset0:132 offset1:134
	v_exp_f32_e32 v140, v53
	v_exp_f32_e32 v141, v54
	v_exp_f32_e32 v142, v55
	v_cvt_pk_bf16_f32 v53, v68, v69
	v_cvt_pk_bf16_f32 v54, v70, v71
	v_cvt_pk_bf16_f32 v55, v72, v73
	v_add_u32_e32 v66, 0x3000, v66
	v_exp_f32_e32 v51, v51
	s_waitcnt lgkmcnt(1)
	v_mfma_f32_32x32x16_bf16 v[18:33], v[56:59], v[52:55], v[18:33]
	v_add3_u32 v253, v252, v185, s33
	s_waitcnt vmcnt(2)
	ds_write2_b64 v253, v[102:103], v[104:105] offset1:1
	global_load_dwordx4 v[102:105], v230, s[24:25]
	ds_read2_b64 v[56:59], v66 offset0:160 offset1:162
	v_exp_f32_e32 v64, v64
	v_exp_f32_e32 v65, v65
	v_add_f32_e32 v50, v51, v50
	v_add_f32_e32 v50, v138, v50
	v_add_f32_e32 v50, v140, v50
	v_add_f32_e32 v50, v141, v50
	s_waitcnt lgkmcnt(0)
	v_mfma_f32_32x32x16_bf16 v[2:17], v[56:59], v[52:55], v[2:17]
	v_add_u32_e32 v253, v252, v180
	s_waitcnt vmcnt(3)
	ds_write_b128 v253, v[106:109]
	global_load_dwordx4 v[106:109], v229, s[12:13]
	ds_read2_b64 v[56:59], v66 offset0:164 offset1:166
	v_cvt_pk_bf16_f32 v52, v74, v75
	v_cvt_pk_bf16_f32 v53, v76, v77
	v_cvt_pk_bf16_f32 v54, v78, v79
	v_cvt_pk_bf16_f32 v55, v80, v81
	v_add_f32_e32 v50, v142, v50
	v_add_f32_e32 v50, v143, v50
	s_waitcnt lgkmcnt(0)
	v_mfma_f32_32x32x16_bf16 v[2:17], v[56:59], v[52:55], v[2:17]
	v_add3_u32 v253, v252, v186, s33
	s_waitcnt vmcnt(3)
	ds_write2_b64 v253, v[110:111], v[112:113] offset1:1
	global_load_dwordx4 v[110:113], v231, s[24:25]
	s_add_u32 s12, s12, 0x2000
	s_addc_u32 s13, s13, 0
	s_add_u32 s24, s24, 0x80
	s_addc_u32 s25, s25, 0
	ds_read2_b64 v[56:59], v67 offset0:136 offset1:138
	v_add_f32_e32 v50, v144, v50
	v_add_f32_e32 v50, v145, v50
	v_add_f32_e32 v50, v147, v50
	v_add_f32_e32 v50, v148, v50
	v_add_f32_e32 v50, v149, v50
	v_add_f32_e32 v50, v150, v50
	v_mfma_f32_32x32x16_bf16 v[18:33], v[60:63], v[52:55], v[18:33]
	v_cvt_pk_bf16_f32 v52, v139, v51
	v_cvt_pk_bf16_f32 v53, v138, v140
	v_cvt_pk_bf16_f32 v54, v141, v142
	v_cvt_pk_bf16_f32 v55, v143, v144
	v_add_f32_e32 v50, v151, v50
	v_add_f32_e32 v50, v64, v50
	v_add_f32_e32 v50, v65, v50
	s_waitcnt lgkmcnt(0)
	v_mfma_f32_32x32x16_bf16 v[18:33], v[56:59], v[52:55], v[18:33]
	ds_read2_b64 v[56:59], v66 offset0:168 offset1:170
	v_add_f32_e32 v136, v136, v50
	v_cmp_lt_f32_e32 vcc, s20, v50
	s_waitcnt lgkmcnt(0)
	v_mfma_f32_32x32x16_bf16 v[2:17], v[56:59], v[52:55], v[2:17]
	ds_read2_b64 v[56:59], v67 offset0:140 offset1:142
	v_cvt_pk_bf16_f32 v52, v145, v147
	v_cvt_pk_bf16_f32 v53, v148, v149
	v_cvt_pk_bf16_f32 v54, v150, v151
	v_cvt_pk_bf16_f32 v55, v64, v65
	s_waitcnt lgkmcnt(0)
	s_nop 0
	v_mfma_f32_32x32x16_bf16 v[18:33], v[56:59], v[52:55], v[18:33]
	ds_read2_b64 v[56:59], v66 offset0:172 offset1:174
	s_waitcnt lgkmcnt(0)
	v_mfma_f32_32x32x16_bf16 v[2:17], v[56:59], v[52:55], v[2:17]
	s_cbranch_vccz .LBB0_938
	v_mov_b32_e32 v34, v50
	s_nop 1
	v_permlane32_swap_b32_e32 v50, v34
	v_add_f32_e32 v34, v50, v34
	v_log_f32_e32 v35, v34
	v_cmp_lt_f32_e32 vcc, s20, v34
	s_nop 1
	v_cndmask_b32_e32 v35, 0, v35, vcc
	v_exp_f32_e64 v34, -v35
	v_add_f32_e32 v0, v0, v35
	v_xor_b32_e32 v49, 0x80000000, v0
	v_mov_b32_e32 v48, v49
	v_mul_f32_e32 v136, v136, v34
	v_pk_mul_f32 v[32:33], v[32:33], v[34:35] op_sel_hi:[1,0]
	v_pk_mul_f32 v[30:31], v[30:31], v[34:35] op_sel_hi:[1,0]
	v_pk_mul_f32 v[28:29], v[28:29], v[34:35] op_sel_hi:[1,0]
	v_pk_mul_f32 v[26:27], v[26:27], v[34:35] op_sel_hi:[1,0]
	v_pk_mul_f32 v[24:25], v[24:25], v[34:35] op_sel_hi:[1,0]
	v_pk_mul_f32 v[22:23], v[22:23], v[34:35] op_sel_hi:[1,0]
	v_pk_mul_f32 v[20:21], v[20:21], v[34:35] op_sel_hi:[1,0]
	v_pk_mul_f32 v[18:19], v[18:19], v[34:35] op_sel_hi:[1,0]
	v_pk_mul_f32 v[16:17], v[16:17], v[34:35] op_sel_hi:[1,0]
	v_pk_mul_f32 v[14:15], v[14:15], v[34:35] op_sel_hi:[1,0]
	v_pk_mul_f32 v[12:13], v[12:13], v[34:35] op_sel_hi:[1,0]
	v_pk_mul_f32 v[10:11], v[10:11], v[34:35] op_sel_hi:[1,0]
	v_pk_mul_f32 v[8:9], v[8:9], v[34:35] op_sel_hi:[1,0]
	v_pk_mul_f32 v[6:7], v[6:7], v[34:35] op_sel_hi:[1,0]
	v_pk_mul_f32 v[4:5], v[4:5], v[34:35] op_sel_hi:[1,0]
	v_pk_mul_f32 v[2:3], v[2:3], v[34:35] op_sel_hi:[1,0]
	v_mov_b32_e32 v47, v49
	v_mov_b32_e32 v46, v49
	v_mov_b32_e32 v45, v49
	v_mov_b32_e32 v44, v49
	v_mov_b32_e32 v43, v49
	v_mov_b32_e32 v42, v49
	v_mov_b32_e32 v41, v49
	v_mov_b32_e32 v40, v49
	v_mov_b32_e32 v39, v49
	v_mov_b32_e32 v38, v49
	v_mov_b32_e32 v37, v49
	v_mov_b32_e32 v36, v49
	v_mov_b32_e32 v35, v49
	v_mov_b32_e32 v34, v49
	s_branch .LBB0_938
